# attention epilogue: the last five combine-buffer reads are also issued together
# speedup vs baseline: 1.0053x; 1.0053x over previous
.LBB0_223:
	s_cmp_gt_i32 s6, 3
	s_waitcnt lgkmcnt(0)
	s_barrier
	s_cbranch_scc1 .LBB0_198
	v_lshlrev_b32_e32 v89, 4, v80
	global_load_dwordx4 v[192:195], v89, s[2:3]
	global_load_dwordx4 v[196:199], v89, s[2:3] offset:32
	global_load_dwordx4 v[200:203], v89, s[2:3] offset:64
	global_load_dwordx4 v[204:207], v89, s[2:3] offset:96
	global_load_dwordx4 v[208:211], v89, s[2:3] offset:128
	global_load_dwordx4 v[212:215], v89, s[2:3] offset:160
	global_load_dwordx4 v[216:219], v89, s[2:3] offset:192
	global_load_dwordx4 v[220:223], v89, s[2:3] offset:224
	global_load_dwordx4 v[224:227], v89, s[2:3] offset:256
	global_load_dwordx4 v[228:231], v89, s[2:3] offset:288
	global_load_dwordx4 v[232:235], v89, s[2:3] offset:320
	global_load_dwordx4 v[236:239], v89, s[2:3] offset:352
	global_load_dwordx4 v[244:247], v89, s[2:3] offset:384
	global_load_dwordx4 v[248:251], v89, s[2:3] offset:416
	global_load_dwordx4 v[252:255], v89, s[2:3] offset:448
	global_load_dwordx4 v[148:151], v89, s[2:3] offset:480
	s_lshl_b32 s6, s5, 14
	v_add3_u32 v2, v7, v6, s6
	ds_read2_b32 v[96:97], v2 offset1:32
	ds_read2_b32 v[98:99], v2 offset0:64 offset1:96
	v_add_u32_e32 v88, 0x400, v2
	ds_read2_b32 v[100:101], v88 offset1:32
	ds_read2_b32 v[102:103], v88 offset0:64 offset1:96
	v_add_u32_e32 v88, 0x800, v2
	ds_read2_b32 v[104:105], v88 offset1:32
	ds_read2_b32 v[106:107], v88 offset0:64 offset1:96
	v_add_u32_e32 v88, 0xc00, v2
	ds_read2_b32 v[108:109], v88 offset1:32
	ds_read2_b32 v[110:111], v88 offset0:64 offset1:96
	s_waitcnt lgkmcnt(7)
	v_fma_f32 v81, v64, v0, -v96
	v_fma_f32 v64, v65, v0, -v97
	v_add_u32_e32 v88, 0x1000, v2
	ds_read2_b32 v[96:97], v88 offset1:32
	s_waitcnt lgkmcnt(7)
	v_fma_f32 v65, v66, v0, -v98
	v_fma_f32 v66, v67, v0, -v99
	ds_read2_b32 v[98:99], v88 offset0:64 offset1:96
	v_mul_f32_e32 v6, v64, v64
	v_fmac_f32_e32 v6, v81, v81
	v_fmac_f32_e32 v6, v65, v65
	v_fmac_f32_e32 v6, v66, v66
	s_waitcnt lgkmcnt(7)
	v_fma_f32 v67, v68, v0, -v100
	v_fma_f32 v68, v69, v0, -v101
	v_add_u32_e32 v88, 0x1400, v2
	ds_read2_b32 v[100:101], v88 offset1:32
	v_fmac_f32_e32 v6, v67, v67
	v_fmac_f32_e32 v6, v68, v68
	s_waitcnt lgkmcnt(7)
	v_fma_f32 v69, v70, v0, -v102
	v_fma_f32 v70, v71, v0, -v103
	ds_read2_b32 v[102:103], v88 offset0:64 offset1:96
	v_fmac_f32_e32 v6, v69, v69
	v_fmac_f32_e32 v6, v70, v70
	s_waitcnt lgkmcnt(7)
	v_fma_f32 v72, v72, v0, -v104
	v_fma_f32 v71, v73, v0, -v105
	v_add_u32_e32 v88, 0x1800, v2
	ds_read2_b32 v[104:105], v88 offset1:32
	v_fmac_f32_e32 v6, v72, v72
	v_fmac_f32_e32 v6, v71, v71
	s_waitcnt lgkmcnt(7)
	v_fma_f32 v82, v74, v0, -v106
	v_fma_f32 v75, v75, v0, -v107
	ds_read2_b32 v[106:107], v88 offset0:64 offset1:96
	v_fmac_f32_e32 v6, v82, v82
	v_fmac_f32_e32 v6, v75, v75
	s_waitcnt lgkmcnt(7)
	v_fma_f32 v74, v76, v0, -v108
	v_fma_f32 v73, v77, v0, -v109
	v_add_u32_e32 v88, 0x1c00, v2
	ds_read2_b32 v[108:109], v88 offset1:32
	v_fmac_f32_e32 v6, v74, v74
	v_fmac_f32_e32 v6, v73, v73
	s_waitcnt lgkmcnt(7)
	v_fma_f32 v78, v78, v0, -v110
	v_fma_f32 v77, v79, v0, -v111
	ds_read2_b32 v[110:111], v88 offset0:64 offset1:96
	v_fmac_f32_e32 v6, v78, v78
	v_fmac_f32_e32 v6, v77, v77
	s_waitcnt lgkmcnt(7)
	v_fma_f32 v76, v48, v0, -v96
	v_fma_f32 v48, v49, v0, -v97
	v_add_u32_e32 v88, 0x2000, v2
	ds_read2_b32 v[96:97], v88 offset1:32
	v_fmac_f32_e32 v6, v76, v76
	v_fmac_f32_e32 v6, v48, v48
	s_waitcnt lgkmcnt(7)
	v_fma_f32 v79, v50, v0, -v98
	v_fma_f32 v51, v51, v0, -v99
	ds_read2_b32 v[98:99], v88 offset0:64 offset1:96
	v_fmac_f32_e32 v6, v79, v79
	v_fmac_f32_e32 v6, v51, v51
	s_waitcnt lgkmcnt(7)
	v_fma_f32 v50, v52, v0, -v100
	v_fma_f32 v49, v53, v0, -v101
	v_add_u32_e32 v88, 0x2400, v2
	ds_read2_b32 v[100:101], v88 offset1:32
	v_fmac_f32_e32 v6, v50, v50
	v_fmac_f32_e32 v6, v49, v49
	s_waitcnt lgkmcnt(7)
	v_fma_f32 v83, v54, v0, -v102
	v_fma_f32 v54, v55, v0, -v103
	ds_read2_b32 v[102:103], v88 offset0:64 offset1:96
	v_fmac_f32_e32 v6, v83, v83
	v_fmac_f32_e32 v6, v54, v54
	s_waitcnt lgkmcnt(7)
	v_fma_f32 v53, v56, v0, -v104
	v_fma_f32 v52, v57, v0, -v105
	v_add_u32_e32 v88, 0x2800, v2
	ds_read2_b32 v[104:105], v88 offset1:32
	v_fmac_f32_e32 v6, v53, v53
	v_fmac_f32_e32 v6, v52, v52
	s_waitcnt lgkmcnt(7)
	v_fma_f32 v58, v58, v0, -v106
	v_fma_f32 v57, v59, v0, -v107
	ds_read2_b32 v[106:107], v88 offset0:64 offset1:96
	v_fmac_f32_e32 v6, v58, v58
	v_fmac_f32_e32 v6, v57, v57
	s_waitcnt lgkmcnt(7)
	v_fma_f32 v56, v60, v0, -v108
	v_fma_f32 v55, v61, v0, -v109
	v_add_u32_e32 v88, 0x2c00, v2
	ds_read2_b32 v[108:109], v88 offset1:32
	v_fmac_f32_e32 v6, v56, v56
	v_fmac_f32_e32 v6, v55, v55
	s_waitcnt lgkmcnt(7)
	v_fma_f32 v61, v62, v0, -v110
	v_fma_f32 v60, v63, v0, -v111
	ds_read2_b32 v[110:111], v88 offset0:64 offset1:96
	v_fmac_f32_e32 v6, v61, v61
	v_fmac_f32_e32 v6, v60, v60
	s_waitcnt lgkmcnt(7)
	v_fma_f32 v59, v32, v0, -v96
	v_fma_f32 v32, v33, v0, -v97
	v_add_u32_e32 v88, 0x3000, v2
	ds_read2_b32 v[96:97], v88 offset1:32
	v_fmac_f32_e32 v6, v59, v59
	v_fmac_f32_e32 v6, v32, v32
	s_waitcnt lgkmcnt(7)
	v_fma_f32 v63, v34, v0, -v98
	v_fma_f32 v62, v35, v0, -v99
	ds_read2_b32 v[98:99], v88 offset0:64 offset1:96
	v_fmac_f32_e32 v6, v63, v63
	v_fmac_f32_e32 v6, v62, v62
	s_waitcnt lgkmcnt(7)
	v_fma_f32 v36, v36, v0, -v100
	v_fma_f32 v34, v37, v0, -v101
	v_add_u32_e32 v88, 0x3400, v2
	ds_read2_b32 v[100:101], v88 offset1:32
	v_fmac_f32_e32 v6, v36, v36
	v_fmac_f32_e32 v6, v34, v34
	s_waitcnt lgkmcnt(7)
	v_fma_f32 v85, v38, v0, -v102
	v_fma_f32 v84, v39, v0, -v103
	v_fmac_f32_e32 v6, v85, v85
	v_fmac_f32_e32 v6, v84, v84
	s_waitcnt lgkmcnt(6)
	v_fma_f32 v40, v40, v0, -v104
	v_fma_f32 v39, v41, v0, -v105
	v_fmac_f32_e32 v6, v40, v40
	v_fmac_f32_e32 v6, v39, v39
	s_waitcnt lgkmcnt(5)
	v_fma_f32 v87, v42, v0, -v106
	v_fma_f32 v86, v43, v0, -v107
	v_fmac_f32_e32 v6, v87, v87
	v_fmac_f32_e32 v6, v86, v86
	s_waitcnt lgkmcnt(4)
	v_fma_f32 v44, v44, v0, -v108
	v_fma_f32 v43, v45, v0, -v109
	v_fmac_f32_e32 v6, v44, v44
	v_fmac_f32_e32 v6, v43, v43
	s_waitcnt lgkmcnt(3)
	v_fma_f32 v42, v46, v0, -v110
	v_fma_f32 v41, v47, v0, -v111
	v_fmac_f32_e32 v6, v42, v42
	v_fmac_f32_e32 v6, v41, v41
	s_waitcnt lgkmcnt(2)
	v_fma_f32 v38, v16, v0, -v96
	v_fma_f32 v37, v17, v0, -v97
	v_fmac_f32_e32 v6, v38, v38
	v_fmac_f32_e32 v6, v37, v37
	s_waitcnt lgkmcnt(1)
	v_fma_f32 v35, v18, v0, -v98
	v_fma_f32 v33, v19, v0, -v99
	v_fmac_f32_e32 v6, v35, v35
	v_fmac_f32_e32 v6, v33, v33
	s_waitcnt lgkmcnt(0)
	v_fma_f32 v20, v20, v0, -v100
	v_fma_f32 v19, v21, v0, -v101
	v_fmac_f32_e32 v6, v20, v20
	v_fmac_f32_e32 v6, v19, v19
	v_add_u32_e32 v88, 0x3400, v2
	ds_read2_b32 v[112:113], v88 offset0:64 offset1:96
	v_add_u32_e32 v88, 0x3800, v2
	ds_read2_b32 v[114:115], v88 offset1:32
	ds_read2_b32 v[116:117], v88 offset0:64 offset1:96
	v_add_u32_e32 v88, 0x3c00, v2
	ds_read2_b32 v[118:119], v88 offset1:32
	ds_read2_b32 v[120:121], v88 offset0:64 offset1:96
	v_lshlrev_b32_e32 v21, 4, v80
	s_waitcnt lgkmcnt(4)
	v_pk_fma_f32 v[14:15], v[22:23], v[0:1], v[112:113] op_sel_hi:[1,0,1] neg_lo:[0,0,1] neg_hi:[0,0,1]
	s_nop 0
	v_pk_mul_f32 v[8:9], v[14:15], v[14:15]
	s_nop 0
	v_add_f32_e32 v6, v6, v8
	v_add_f32_e32 v8, v6, v9
	v_add_u32_e32 v9, 0x3800, v2
	v_add_u32_e32 v2, 0x3c00, v2
	s_waitcnt lgkmcnt(3)
	v_pk_fma_f32 v[12:13], v[24:25], v[0:1], v[114:115] op_sel_hi:[1,0,1] neg_lo:[0,0,1] neg_hi:[0,0,1]
	s_nop 0
	v_pk_mul_f32 v[6:7], v[12:13], v[12:13]
	s_nop 0
	v_add_f32_e32 v6, v8, v6
	v_add_f32_e32 v8, v6, v7
	s_waitcnt lgkmcnt(2)
	v_pk_fma_f32 v[10:11], v[26:27], v[0:1], v[116:117] op_sel_hi:[1,0,1] neg_lo:[0,0,1] neg_hi:[0,0,1]
	s_nop 0
	v_pk_mul_f32 v[6:7], v[10:11], v[10:11]
	s_nop 0
	v_add_f32_e32 v6, v8, v6
	v_add_f32_e32 v16, v6, v7
	s_waitcnt lgkmcnt(1)
	v_pk_fma_f32 v[8:9], v[28:29], v[0:1], v[118:119] op_sel_hi:[1,0,1] neg_lo:[0,0,1] neg_hi:[0,0,1]
	s_nop 0
	v_pk_mul_f32 v[6:7], v[8:9], v[8:9]
	s_nop 0
	v_add_f32_e32 v6, v16, v6
	v_add_f32_e32 v18, v6, v7
	s_waitcnt lgkmcnt(0)
	v_pk_fma_f32 v[6:7], v[30:31], v[0:1], v[120:121] op_sel_hi:[1,0,1] neg_lo:[0,0,1] neg_hi:[0,0,1]
	s_nop 0
	v_pk_mul_f32 v[16:17], v[6:7], v[6:7]
	s_nop 0
	v_add_f32_e32 v0, v18, v16
	v_add_f32_e32 v0, v0, v17
	ds_bpermute_b32 v2, v5, v0
	s_waitcnt lgkmcnt(0)
	v_add_f32_e32 v0, v0, v2
	v_fmamk_f32 v0, v0, 0x3c000000, v174
	v_cmp_gt_f32_e32 vcc, s90, v0
	v_mul_f32_e32 v2, 0x4b800000, v0
	s_nop 0
	v_cndmask_b32_e32 v0, v0, v2, vcc
	v_rsq_f32_e32 v0, v0
	s_nop 0
	v_mul_f32_e32 v2, 0x45800000, v0
	v_cndmask_b32_e32 v0, v0, v2, vcc
	v_mul_f32_e32 v18, v3, v0
	v_lshl_or_b32 v0, s5, 5, v4
	v_or_b32_e32 v0, s22, v0
	v_lshlrev_b64 v[2:3], 11, v[0:1]
	v_lshl_add_u64 v[2:3], s[84:85], 0, v[2:3]
	s_mov_b32 s5, s81
	v_lshl_add_u64 v[16:17], v[2:3], 0, s[4:5]
	s_nop 0
	v_mul_f32_e32 v0, v81, v18
	s_waitcnt vmcnt(0)
	v_mov_b32_e32 v2, v192
	v_mov_b32_e32 v3, v193
	v_mov_b32_e32 v4, v194
	v_mov_b32_e32 v5, v195
	s_nop 0
	v_mul_f32_e32 v0, v2, v0
	v_mul_f32_e32 v2, v64, v18
	v_mul_f32_e32 v2, v3, v2
	v_cvt_pk_bf16_f32 v22, v0, v2
	v_mul_f32_e32 v0, v65, v18
	v_mul_f32_e32 v0, v4, v0
	v_mul_f32_e32 v2, v66, v18
	v_mul_f32_e32 v2, v5, v2
	v_cvt_pk_bf16_f32 v23, v0, v2
	v_lshlrev_b32_e32 v0, 3, v80
	v_lshl_add_u64 v[2:3], v[16:17], 0, v[0:1]
	global_store_dwordx2 v[2:3], v[22:23], off
	s_nop 0
	v_mul_f32_e32 v0, v67, v18
	v_mul_f32_e32 v4, v68, v18
	v_mul_f32_e32 v5, v70, v18
	s_nop 1
	v_mov_b32_e32 v22, v196
	v_mov_b32_e32 v23, v197
	v_mov_b32_e32 v24, v198
	v_mov_b32_e32 v25, v199
	s_nop 0
	v_mul_f32_e32 v0, v22, v0
	v_mul_f32_e32 v4, v23, v4
	v_cvt_pk_bf16_f32 v4, v0, v4
	v_mul_f32_e32 v0, v69, v18
	v_mul_f32_e32 v5, v25, v5
	v_mul_f32_e32 v0, v24, v0
	v_cvt_pk_bf16_f32 v5, v0, v5
	global_store_dwordx2 v[2:3], v[4:5], off offset:16
	s_nop 0
	v_mul_f32_e32 v0, v72, v18
	v_mul_f32_e32 v4, v71, v18
	v_mul_f32_e32 v5, v75, v18
	s_nop 1
	v_mov_b32_e32 v22, v200
	v_mov_b32_e32 v23, v201
	v_mov_b32_e32 v24, v202
	v_mov_b32_e32 v25, v203
	s_nop 0
	v_mul_f32_e32 v0, v22, v0
	v_mul_f32_e32 v4, v23, v4
	v_cvt_pk_bf16_f32 v4, v0, v4
	v_mul_f32_e32 v0, v82, v18
	v_mul_f32_e32 v5, v25, v5
	v_mul_f32_e32 v0, v24, v0
	v_cvt_pk_bf16_f32 v5, v0, v5
	global_store_dwordx2 v[2:3], v[4:5], off offset:32
	s_nop 0
	v_mul_f32_e32 v0, v74, v18
	v_mul_f32_e32 v4, v73, v18
	v_mul_f32_e32 v5, v77, v18
	s_nop 1
	v_mov_b32_e32 v22, v204
	v_mov_b32_e32 v23, v205
	v_mov_b32_e32 v24, v206
	v_mov_b32_e32 v25, v207
	s_nop 0
	v_mul_f32_e32 v0, v0, v22
	v_mul_f32_e32 v4, v4, v23
	v_cvt_pk_bf16_f32 v4, v0, v4
	v_mul_f32_e32 v0, v78, v18
	v_mul_f32_e32 v5, v5, v25
	v_mul_f32_e32 v0, v0, v24
	v_cvt_pk_bf16_f32 v5, v0, v5
	global_store_dwordx2 v[2:3], v[4:5], off offset:48
	s_nop 0
	v_mul_f32_e32 v0, v76, v18
	v_mul_f32_e32 v4, v48, v18
	v_mul_f32_e32 v5, v51, v18
	s_nop 1
	v_mov_b32_e32 v22, v208
	v_mov_b32_e32 v23, v209
	v_mov_b32_e32 v24, v210
	v_mov_b32_e32 v25, v211
	s_nop 0
	v_mul_f32_e32 v0, v0, v22
	v_mul_f32_e32 v4, v4, v23
	v_cvt_pk_bf16_f32 v4, v0, v4
	v_mul_f32_e32 v0, v79, v18
	v_mul_f32_e32 v5, v5, v25
	v_mul_f32_e32 v0, v0, v24
	v_cvt_pk_bf16_f32 v5, v0, v5
	global_store_dwordx2 v[2:3], v[4:5], off offset:64
	s_nop 0
	v_mul_f32_e32 v0, v50, v18
	v_mul_f32_e32 v4, v49, v18
	v_mul_f32_e32 v5, v54, v18
	s_nop 1
	v_mov_b32_e32 v22, v212
	v_mov_b32_e32 v23, v213
	v_mov_b32_e32 v24, v214
	v_mov_b32_e32 v25, v215
	s_nop 0
	v_mul_f32_e32 v0, v0, v22
	v_mul_f32_e32 v4, v4, v23
	v_cvt_pk_bf16_f32 v4, v0, v4
	v_mul_f32_e32 v0, v83, v18
	v_mul_f32_e32 v5, v5, v25
	v_mul_f32_e32 v0, v0, v24
	v_cvt_pk_bf16_f32 v5, v0, v5
	global_store_dwordx2 v[2:3], v[4:5], off offset:80
	s_nop 0
	v_mul_f32_e32 v0, v53, v18
	v_mul_f32_e32 v4, v52, v18
	v_mul_f32_e32 v5, v57, v18
	s_nop 1
	v_mov_b32_e32 v22, v216
	v_mov_b32_e32 v23, v217
	v_mov_b32_e32 v24, v218
	v_mov_b32_e32 v25, v219
	s_nop 0
	v_mul_f32_e32 v0, v0, v22
	v_mul_f32_e32 v4, v4, v23
	v_cvt_pk_bf16_f32 v4, v0, v4
	v_mul_f32_e32 v0, v58, v18
	v_mul_f32_e32 v5, v5, v25
	v_mul_f32_e32 v0, v0, v24
	v_cvt_pk_bf16_f32 v5, v0, v5
	global_store_dwordx2 v[2:3], v[4:5], off offset:96
	s_nop 0
	v_mul_f32_e32 v0, v56, v18
	v_mul_f32_e32 v4, v55, v18
	v_mul_f32_e32 v5, v60, v18
	s_nop 1
	v_mov_b32_e32 v22, v220
	v_mov_b32_e32 v23, v221
	v_mov_b32_e32 v24, v222
	v_mov_b32_e32 v25, v223
	s_nop 0
	v_mul_f32_e32 v0, v0, v22
	v_mul_f32_e32 v4, v4, v23
	v_cvt_pk_bf16_f32 v4, v0, v4
	v_mul_f32_e32 v0, v61, v18
	v_mul_f32_e32 v5, v5, v25
	v_mul_f32_e32 v0, v0, v24
	v_cvt_pk_bf16_f32 v5, v0, v5
	global_store_dwordx2 v[2:3], v[4:5], off offset:112
	s_nop 0
	v_mul_f32_e32 v0, v59, v18
	v_mul_f32_e32 v4, v32, v18
	v_mul_f32_e32 v5, v62, v18
	s_nop 1
	v_mov_b32_e32 v22, v224
	v_mov_b32_e32 v23, v225
	v_mov_b32_e32 v24, v226
	v_mov_b32_e32 v25, v227
	s_nop 0
	v_mul_f32_e32 v0, v0, v22
	v_mul_f32_e32 v4, v4, v23
	v_cvt_pk_bf16_f32 v4, v0, v4
	v_mul_f32_e32 v0, v63, v18
	v_mul_f32_e32 v5, v5, v25
	v_mul_f32_e32 v0, v0, v24
	v_cvt_pk_bf16_f32 v5, v0, v5
	global_store_dwordx2 v[2:3], v[4:5], off offset:128
	s_nop 0
	v_mul_f32_e32 v0, v36, v18
	v_mul_f32_e32 v4, v34, v18
	v_mul_f32_e32 v5, v84, v18
	s_nop 1
	v_mov_b32_e32 v22, v228
	v_mov_b32_e32 v23, v229
	v_mov_b32_e32 v24, v230
	v_mov_b32_e32 v25, v231
	s_nop 0
	v_mul_f32_e32 v0, v0, v22
	v_mul_f32_e32 v4, v4, v23
	v_cvt_pk_bf16_f32 v4, v0, v4
	v_mul_f32_e32 v0, v85, v18
	v_mul_f32_e32 v5, v5, v25
	v_mul_f32_e32 v0, v0, v24
	v_cvt_pk_bf16_f32 v5, v0, v5
	global_store_dwordx2 v[2:3], v[4:5], off offset:144
	s_nop 0
	v_mul_f32_e32 v0, v40, v18
	v_mul_f32_e32 v4, v39, v18
	v_mul_f32_e32 v5, v86, v18
	s_nop 1
	v_mov_b32_e32 v22, v232
	v_mov_b32_e32 v23, v233
	v_mov_b32_e32 v24, v234
	v_mov_b32_e32 v25, v235
	s_nop 0
	v_mul_f32_e32 v0, v0, v22
	v_mul_f32_e32 v4, v4, v23
	v_cvt_pk_bf16_f32 v4, v0, v4
	v_mul_f32_e32 v0, v87, v18
	v_mul_f32_e32 v5, v5, v25
	v_mul_f32_e32 v0, v0, v24
	v_cvt_pk_bf16_f32 v5, v0, v5
	global_store_dwordx2 v[2:3], v[4:5], off offset:160
	s_nop 0
	v_mul_f32_e32 v0, v44, v18
	v_mul_f32_e32 v4, v43, v18
	v_mul_f32_e32 v5, v41, v18
	s_nop 1
	v_mov_b32_e32 v22, v236
	v_mov_b32_e32 v23, v237
	v_mov_b32_e32 v24, v238
	v_mov_b32_e32 v25, v239
	s_nop 0
	v_mul_f32_e32 v0, v0, v22
	v_mul_f32_e32 v4, v4, v23
	v_cvt_pk_bf16_f32 v4, v0, v4
	v_mul_f32_e32 v0, v42, v18
	v_mul_f32_e32 v5, v5, v25
	v_mul_f32_e32 v0, v0, v24
	v_cvt_pk_bf16_f32 v5, v0, v5
	global_store_dwordx2 v[2:3], v[4:5], off offset:176
	s_nop 0
	v_mul_f32_e32 v0, v38, v18
	v_mul_f32_e32 v4, v37, v18
	v_mul_f32_e32 v5, v33, v18
	s_nop 1
	v_mov_b32_e32 v22, v244
	v_mov_b32_e32 v23, v245
	v_mov_b32_e32 v24, v246
	v_mov_b32_e32 v25, v247
	s_nop 0
	v_mul_f32_e32 v0, v0, v22
	v_mul_f32_e32 v4, v4, v23
	v_cvt_pk_bf16_f32 v4, v0, v4
	v_mul_f32_e32 v0, v35, v18
	v_mul_f32_e32 v5, v5, v25
	v_mul_f32_e32 v0, v0, v24
	v_cvt_pk_bf16_f32 v5, v0, v5
	global_store_dwordx2 v[2:3], v[4:5], off offset:192
	s_nop 0
	v_mul_f32_e32 v0, v20, v18
	v_mul_f32_e32 v4, v19, v18
	v_mul_f32_e32 v5, v15, v18
	s_nop 1
	v_mov_b32_e32 v22, v248
	v_mov_b32_e32 v23, v249
	v_mov_b32_e32 v24, v250
	v_mov_b32_e32 v25, v251
	s_nop 0
	v_mul_f32_e32 v0, v0, v22
	v_mul_f32_e32 v4, v4, v23
	v_cvt_pk_bf16_f32 v4, v0, v4
	v_mul_f32_e32 v0, v14, v18
	v_mul_f32_e32 v5, v5, v25
	v_mul_f32_e32 v0, v0, v24
	v_cvt_pk_bf16_f32 v5, v0, v5
	global_store_dwordx2 v[2:3], v[4:5], off offset:208
	s_nop 0
	v_mul_f32_e32 v0, v12, v18
	v_mul_f32_e32 v4, v13, v18
	v_mul_f32_e32 v5, v11, v18
	s_nop 1
	v_mov_b32_e32 v14, v252
	v_mov_b32_e32 v15, v253
	v_mov_b32_e32 v16, v254
	v_mov_b32_e32 v17, v255
	s_nop 0
	v_mul_f32_e32 v0, v0, v14
	v_mul_f32_e32 v4, v4, v15
	v_cvt_pk_bf16_f32 v4, v0, v4
	v_mul_f32_e32 v0, v10, v18
	v_mul_f32_e32 v5, v5, v17
	v_mul_f32_e32 v0, v0, v16
	v_cvt_pk_bf16_f32 v5, v0, v5
	global_store_dwordx2 v[2:3], v[4:5], off offset:224
	s_nop 0
	v_mul_f32_e32 v0, v8, v18
	v_mul_f32_e32 v4, v9, v18
	v_mul_f32_e32 v5, v7, v18
	s_nop 1
	v_mov_b32_e32 v10, v148
	v_mov_b32_e32 v11, v149
	v_mov_b32_e32 v12, v150
	v_mov_b32_e32 v13, v151
	s_nop 0
	v_mul_f32_e32 v0, v0, v10
	v_mul_f32_e32 v4, v4, v11
	v_cvt_pk_bf16_f32 v4, v0, v4
	v_mul_f32_e32 v0, v6, v18
	v_mul_f32_e32 v5, v5, v13
	v_mul_f32_e32 v0, v0, v12
	v_cvt_pk_bf16_f32 v5, v0, v5
	global_store_dwordx2 v[2:3], v[4:5], off offset:240
	s_branch .LBB0_198
